# FFN2 weight conversion moved from norm phase into idle workgroups of the in-projection GEMM; MLA loop one barrier per two key tiles
# speedup vs baseline: 1.0459x; 1.0064x over previous
; #define PIN(i) gptr(lds, (i))
; #define lds fresh_lds(lds0)
; __global__ void __launch_bounds__(512) mega_fwd(Params P) {
;     ...
;         norm_rows(X, PIN(5) + L * DM, HN, gw, NGW, lane);
;         conv_ffn(PIN(20) + (size_t)L * DM * DFF, PIN(21) + (size_t)L * DM * DFF, PIN(22) + (size_t)L * DFF * DM, Wgu, Wd, scr, gw, NGW, lane); }
;         gsync(lds);
.Ln2_done:
	v_writelane_b32 v254, s12, 11
	s_nop 1
	v_writelane_b32 v254, s13, 12
	v_writelane_b32 v254, s14, 13
	v_writelane_b32 v254, s15, 14
	s_branch .LBB0_546

; template <class F>
; DI void conv_matrix(const F& f, int K, int Nd, bf16_t* dst, LAS float* scr, int gw, int NGW, int lane) {
;     ...
;     for (int it = gw; it < items; it += NGW) {
;         const int kb = it / nblk, nb = it % nblk, k0 = 64 * kb, n0 = 32 * nb;
; float tmp_[32];
; #pragma unroll
;         for (int i = 0; i < 32; ++i) tmp_[i] = f(n0 + (lane & 31), k0 + 2 * i + (lane >> 5));
; #pragma unroll
;         for (int i = 0; i < 32; ++i) scr[(2 * i + (lane >> 5)) * 33 + (lane & 31)] = tmp_[i];
.LBB0_545:
	s_ashr_i32 s0, s7, 31
	s_lshr_b32 s0, s0, 27
	s_add_i32 s0, s7, s0
	s_ashr_i32 s1, s0, 5
	s_lshl_b32 s0, s1, 6
	s_lshl_b32 s8, s1, 10
	v_or_b32_e32 v18, s0, v60
	v_subrev_u32_e32 v16, s8, v62
	v_or_b32_e32 v6, 4, v18
	v_or_b32_e32 v8, 6, v18
	v_or_b32_e32 v10, 8, v18
	v_or_b32_e32 v22, 16, v18
	v_or_b32_e32 v24, 18, v18
	v_or_b32_e32 v26, 20, v18
	v_or_b32_e32 v28, 22, v18
	v_or_b32_e32 v30, 24, v18
	v_or_b32_e32 v32, 26, v18
	v_or_b32_e32 v34, 28, v18
	v_or_b32_e32 v36, 30, v18
	v_or_b32_e32 v38, 32, v18
	v_or_b32_e32 v40, 34, v18
	v_or_b32_e32 v42, 36, v18
	v_or_b32_e32 v44, 38, v18
	v_ashrrev_i32_e32 v17, 31, v16
	v_ashrrev_i32_e32 v19, 31, v18
	v_or_b32_e32 v4, 2, v18
	v_or_b32_e32 v12, 10, v18
	v_or_b32_e32 v14, 12, v18
	v_or_b32_e32 v20, 14, v18
	v_or_b32_e32 v46, 40, v18
	v_or_b32_e32 v48, 42, v18
	v_or_b32_e32 v50, 44, v18
	v_or_b32_e32 v52, 46, v18
	v_or_b32_e32 v54, 48, v18
	v_or_b32_e32 v56, 50, v18
	v_or_b32_e32 v64, 52, v18
	v_or_b32_e32 v66, 54, v18
	v_or_b32_e32 v68, 56, v18
	v_or_b32_e32 v70, 58, v18
	v_or_b32_e32 v72, 60, v18
	v_or_b32_e32 v58, 62, v18
	v_ashrrev_i32_e32 v7, 31, v6
	v_ashrrev_i32_e32 v9, 31, v8
	v_ashrrev_i32_e32 v11, 31, v10
	v_ashrrev_i32_e32 v23, 31, v22
	v_ashrrev_i32_e32 v25, 31, v24
	v_ashrrev_i32_e32 v27, 31, v26
	v_ashrrev_i32_e32 v29, 31, v28
	v_ashrrev_i32_e32 v31, 31, v30
	v_ashrrev_i32_e32 v33, 31, v32
	v_ashrrev_i32_e32 v35, 31, v34
	v_ashrrev_i32_e32 v37, 31, v36
	v_ashrrev_i32_e32 v39, 31, v38
	v_ashrrev_i32_e32 v41, 31, v40
	v_ashrrev_i32_e32 v43, 31, v42
	v_ashrrev_i32_e32 v45, 31, v44
	v_lshl_add_u64 v[16:17], v[16:17], 2, s[4:5]
	v_lshlrev_b64 v[18:19], 12, v[18:19]
	v_ashrrev_i32_e32 v5, 31, v4
	v_ashrrev_i32_e32 v13, 31, v12
	v_ashrrev_i32_e32 v15, 31, v14
	v_ashrrev_i32_e32 v21, 31, v20
	v_ashrrev_i32_e32 v47, 31, v46
	v_ashrrev_i32_e32 v49, 31, v48
	v_ashrrev_i32_e32 v51, 31, v50
	v_ashrrev_i32_e32 v53, 31, v52
	v_ashrrev_i32_e32 v55, 31, v54
	v_ashrrev_i32_e32 v57, 31, v56
	v_ashrrev_i32_e32 v65, 31, v64
	v_ashrrev_i32_e32 v67, 31, v66
	v_ashrrev_i32_e32 v69, 31, v68
	v_ashrrev_i32_e32 v71, 31, v70
	v_ashrrev_i32_e32 v73, 31, v72
	v_ashrrev_i32_e32 v59, 31, v58
	v_lshlrev_b64 v[6:7], 12, v[6:7]
	v_lshlrev_b64 v[8:9], 12, v[8:9]
	v_lshlrev_b64 v[10:11], 12, v[10:11]
	v_lshlrev_b64 v[22:23], 12, v[22:23]
	v_lshlrev_b64 v[24:25], 12, v[24:25]
	v_lshlrev_b64 v[26:27], 12, v[26:27]
	v_lshlrev_b64 v[28:29], 12, v[28:29]
	v_lshlrev_b64 v[30:31], 12, v[30:31]
	v_lshlrev_b64 v[32:33], 12, v[32:33]
	v_lshlrev_b64 v[34:35], 12, v[34:35]
	v_lshlrev_b64 v[36:37], 12, v[36:37]
	v_lshlrev_b64 v[38:39], 12, v[38:39]
	v_lshlrev_b64 v[40:41], 12, v[40:41]
	v_lshlrev_b64 v[42:43], 12, v[42:43]
	v_lshlrev_b64 v[44:45], 12, v[44:45]
	v_lshl_add_u64 v[18:19], v[16:17], 0, v[18:19]
	v_lshlrev_b64 v[4:5], 12, v[4:5]
	v_lshlrev_b64 v[12:13], 12, v[12:13]
	v_lshlrev_b64 v[14:15], 12, v[14:15]
	v_lshlrev_b64 v[20:21], 12, v[20:21]
	v_lshlrev_b64 v[46:47], 12, v[46:47]
	v_lshlrev_b64 v[48:49], 12, v[48:49]
	v_lshlrev_b64 v[50:51], 12, v[50:51]
	v_lshlrev_b64 v[52:53], 12, v[52:53]
	v_lshlrev_b64 v[54:55], 12, v[54:55]
	v_lshlrev_b64 v[56:57], 12, v[56:57]
	v_lshlrev_b64 v[64:65], 12, v[64:65]
	v_lshlrev_b64 v[66:67], 12, v[66:67]
	v_lshlrev_b64 v[68:69], 12, v[68:69]
	v_lshlrev_b64 v[70:71], 12, v[70:71]
	v_lshlrev_b64 v[72:73], 12, v[72:73]
	v_lshlrev_b64 v[58:59], 12, v[58:59]
	v_lshl_add_u64 v[6:7], v[16:17], 0, v[6:7]
	v_lshl_add_u64 v[8:9], v[16:17], 0, v[8:9]
	v_lshl_add_u64 v[10:11], v[16:17], 0, v[10:11]
	v_lshl_add_u64 v[22:23], v[16:17], 0, v[22:23]
	v_lshl_add_u64 v[24:25], v[16:17], 0, v[24:25]
	v_lshl_add_u64 v[26:27], v[16:17], 0, v[26:27]
	v_lshl_add_u64 v[28:29], v[16:17], 0, v[28:29]
	v_lshl_add_u64 v[30:31], v[16:17], 0, v[30:31]
	v_lshl_add_u64 v[32:33], v[16:17], 0, v[32:33]
	v_lshl_add_u64 v[34:35], v[16:17], 0, v[34:35]
	v_lshl_add_u64 v[36:37], v[16:17], 0, v[36:37]
	v_lshl_add_u64 v[38:39], v[16:17], 0, v[38:39]
	v_lshl_add_u64 v[40:41], v[16:17], 0, v[40:41]
	v_lshl_add_u64 v[42:43], v[16:17], 0, v[42:43]
	v_lshl_add_u64 v[44:45], v[16:17], 0, v[44:45]
	v_lshl_add_u64 v[74:75], v[16:17], 0, v[4:5]
	v_lshl_add_u64 v[12:13], v[16:17], 0, v[12:13]
	v_lshl_add_u64 v[14:15], v[16:17], 0, v[14:15]
	v_lshl_add_u64 v[20:21], v[16:17], 0, v[20:21]
	v_lshl_add_u64 v[46:47], v[16:17], 0, v[46:47]
	v_lshl_add_u64 v[48:49], v[16:17], 0, v[48:49]
	v_lshl_add_u64 v[50:51], v[16:17], 0, v[50:51]
	v_lshl_add_u64 v[52:53], v[16:17], 0, v[52:53]
	v_lshl_add_u64 v[54:55], v[16:17], 0, v[54:55]
	v_lshl_add_u64 v[56:57], v[16:17], 0, v[56:57]
	v_lshl_add_u64 v[64:65], v[16:17], 0, v[64:65]
	v_lshl_add_u64 v[66:67], v[16:17], 0, v[66:67]
	v_lshl_add_u64 v[68:69], v[16:17], 0, v[68:69]
	v_lshl_add_u64 v[70:71], v[16:17], 0, v[70:71]
	v_lshl_add_u64 v[72:73], v[16:17], 0, v[72:73]
	v_lshl_add_u64 v[16:17], v[16:17], 0, v[58:59]
	flat_load_dword v4, v[18:19] nt
	flat_load_dword v5, v[74:75] nt
	s_nop 0
	flat_load_dword v6, v[6:7] nt
	s_nop 0
	flat_load_dword v7, v[8:9] nt
	s_nop 0
	flat_load_dword v8, v[10:11] nt
	flat_load_dword v9, v[12:13] nt
	s_nop 0
	flat_load_dword v10, v[14:15] nt
	flat_load_dword v11, v[20:21] nt
	s_nop 0
	flat_load_dword v22, v[22:23] nt
	s_nop 0
	flat_load_dword v23, v[24:25] nt
	s_nop 0
	flat_load_dword v24, v[26:27] nt
	flat_load_dword v25, v[28:29] nt
	s_nop 0
	flat_load_dword v26, v[30:31] nt
	flat_load_dword v27, v[32:33] nt
	flat_load_dword v28, v[34:35] nt
	flat_load_dword v29, v[36:37] nt
	s_nop 0
	flat_load_dword v30, v[38:39] nt
	flat_load_dword v31, v[40:41] nt
	flat_load_dword v32, v[42:43] nt
	flat_load_dword v33, v[44:45] nt
	flat_load_dword v34, v[46:47] nt
	flat_load_dword v35, v[48:49] nt
	flat_load_dword v36, v[50:51] nt
	flat_load_dword v37, v[52:53] nt
	flat_load_dword v38, v[54:55] nt
	flat_load_dword v39, v[56:57] nt
	flat_load_dword v40, v[64:65] nt
	flat_load_dword v41, v[66:67] nt
	flat_load_dword v42, v[68:69] nt
	flat_load_dword v43, v[70:71] nt
	flat_load_dword v44, v[72:73] nt
	flat_load_dword v45, v[16:17] nt
	v_add_u32_e32 v46, 0x400, v63
	v_add_u32_e32 v47, 0x800, v63
	v_add_u32_e32 v48, 0xc00, v63
	v_add_u32_e32 v49, 0x1000, v63
	v_add_u32_e32 v50, 0x1400, v63
	v_add_u32_e32 v51, 0x1800, v63
	v_add_u32_e32 v52, 0x1c00, v63
	s_waitcnt vmcnt(0) lgkmcnt(0)
; #define LAS __attribute__((address_space(3)))
; DI unsigned cvtpk(float lo, float hi) { f32x2 v = {lo, hi}; bf16x2_t b = __builtin_convertvector(v, bf16x2_t); return __builtin_bit_cast(unsigned, b); }
; template <class F>
; DI void conv_matrix(const F& f, int K, int Nd, bf16_t* dst, LAS float* scr, int gw, int NGW, int lane) {
;     ...
;         for (int i = 0; i < 32; ++i) scr[(2 * i + (lane >> 5)) * 33 + (lane & 31)] = tmp_[i];
;         asm volatile("s_waitcnt lgkmcnt(0)" ::: "memory");
;         const int c = lane & 7;
; #pragma unroll
;         for (int j = 0; j < 4; ++j) { const int n = (lane >> 3) + 8 * j; const LAS float* s = scr + (8 * c) * 33 + n;
;             u32x4 o; o.x = cvtpk(s[0 * 33], s[1 * 33]); o.y = cvtpk(s[2 * 33], s[3 * 33]); o.z = cvtpk(s[4 * 33], s[5 * 33]); o.w = cvtpk(s[6 * 33], s[7 * 33]);
;             *(u32x4*)(dst + (size_t)(n0 + n) * K + k0 + 8 * c) = o; }
;         asm volatile("s_waitcnt lgkmcnt(0)" ::: "memory");
;     }
	ds_write2_b32 v63, v4, v5 offset1:66
	ds_write2_b32 v63, v6, v7 offset0:132 offset1:198
	ds_write2_b32 v46, v8, v9 offset0:8 offset1:74
	ds_write2_b32 v46, v10, v11 offset0:140 offset1:206
	ds_write2_b32 v47, v22, v23 offset0:16 offset1:82
	ds_write2_b32 v47, v24, v25 offset0:148 offset1:214
	ds_write2_b32 v48, v26, v27 offset0:24 offset1:90
	ds_write2_b32 v48, v28, v29 offset0:156 offset1:222
	ds_write2_b32 v49, v30, v31 offset0:32 offset1:98
	ds_write2_b32 v49, v32, v33 offset0:164 offset1:230
	ds_write2_b32 v50, v34, v35 offset0:40 offset1:106
	ds_write2_b32 v50, v36, v37 offset0:172 offset1:238
	ds_write2_b32 v51, v38, v39 offset0:48 offset1:114
	ds_write2_b32 v51, v40, v41 offset0:180 offset1:246
	ds_write2_b32 v52, v42, v43 offset0:56 offset1:122
	ds_write2_b32 v52, v44, v45 offset0:188 offset1:254
	s_waitcnt lgkmcnt(0)
	ds_read_b32 v4, v0
	ds_read_b32 v5, v0 offset:132
	ds_read_b32 v6, v0 offset:264
	ds_read_b32 v7, v0 offset:396
	ds_read_b32 v8, v0 offset:528
	ds_read_b32 v9, v0 offset:660
	ds_read_b32 v10, v0 offset:792
	ds_read_b32 v11, v0 offset:924
	s_mul_i32 s8, s1, 0xffd40000
	s_ashr_i32 s1, s0, 31
	v_add_u32_e32 v12, s8, v61
	v_lshl_add_u64 v[14:15], s[0:1], 1, v[2:3]
	v_ashrrev_i32_e32 v13, 31, v12
	v_add_u32_e32 v16, 0x5800, v12
	v_add_u32_e32 v18, 0xb000, v12
	v_add_u32_e32 v20, 0x10800, v12
	v_lshl_add_u64 v[12:13], v[12:13], 1, v[14:15]
	s_waitcnt lgkmcnt(6)
	v_cvt_pk_bf16_f32 v4, v4, v5
	s_waitcnt lgkmcnt(4)
	v_cvt_pk_bf16_f32 v5, v6, v7
	s_waitcnt lgkmcnt(2)
	v_cvt_pk_bf16_f32 v6, v8, v9
	s_waitcnt lgkmcnt(0)
	v_cvt_pk_bf16_f32 v7, v10, v11
	flat_store_dwordx4 v[12:13], v[4:7]
	ds_read_b32 v4, v0 offset:32
	ds_read_b32 v5, v0 offset:164
	ds_read_b32 v6, v0 offset:296
	ds_read_b32 v7, v0 offset:428
	ds_read_b32 v8, v0 offset:560
	ds_read_b32 v9, v0 offset:692
	ds_read_b32 v10, v0 offset:824
	ds_read_b32 v11, v0 offset:956
	v_ashrrev_i32_e32 v17, 31, v16
	v_lshl_add_u64 v[16:17], v[16:17], 1, v[14:15]
	s_waitcnt lgkmcnt(0)
	v_cvt_pk_bf16_f32 v4, v4, v5
	v_cvt_pk_bf16_f32 v5, v6, v7
	v_cvt_pk_bf16_f32 v6, v8, v9
	v_cvt_pk_bf16_f32 v7, v10, v11
	flat_store_dwordx4 v[16:17], v[4:7]
	ds_read_b32 v4, v0 offset:64
	ds_read_b32 v5, v0 offset:196
	ds_read_b32 v6, v0 offset:328
	ds_read_b32 v7, v0 offset:460
	ds_read_b32 v8, v0 offset:592
	ds_read_b32 v9, v0 offset:724
	ds_read_b32 v10, v0 offset:856
	ds_read_b32 v11, v0 offset:988
	v_ashrrev_i32_e32 v19, 31, v18
	v_lshl_add_u64 v[18:19], v[18:19], 1, v[14:15]
	s_waitcnt lgkmcnt(0)
	v_cvt_pk_bf16_f32 v4, v4, v5
	v_cvt_pk_bf16_f32 v5, v6, v7
	v_cvt_pk_bf16_f32 v6, v8, v9
	v_cvt_pk_bf16_f32 v7, v10, v11
	flat_store_dwordx4 v[18:19], v[4:7]
	ds_read_b32 v4, v0 offset:96
	ds_read_b32 v5, v0 offset:228
	ds_read_b32 v6, v0 offset:360
	ds_read_b32 v7, v0 offset:492
	ds_read_b32 v10, v0 offset:624
	ds_read_b32 v11, v0 offset:756
	ds_read_b32 v12, v0 offset:888
	ds_read_b32 v13, v0 offset:1020
	v_ashrrev_i32_e32 v21, 31, v20
	v_lshl_add_u64 v[8:9], v[20:21], 1, v[14:15]
	s_waitcnt lgkmcnt(0)
	v_cvt_pk_bf16_f32 v4, v4, v5
	v_cvt_pk_bf16_f32 v5, v6, v7
	v_cvt_pk_bf16_f32 v6, v10, v11
	v_cvt_pk_bf16_f32 v7, v12, v13
	flat_store_dwordx4 v[8:9], v[4:7]
	s_waitcnt lgkmcnt(0)
	s_add_i32 s7, s7, s6
	v_add_u32_e32 v61, s2, v61
	s_cmpk_lt_i32 s7, 0x580
	v_add_u32_e32 v62, s3, v62
	s_cbranch_scc1 .LBB0_545
.Lconv_ffn_end:
	s_branch .Lin_conv_ret
.LBB0_546:
	v_readlane_b32 s0, v254, 11
	v_readlane_b32 s1, v254, 12
	s_mov_b32 s60, s1
	s_add_i32 s0, s60, 0x20040
	v_mov_b32_e32 v0, s0
	ds_read_b32 v2, v0 offset:200
	ds_read_b32 v0, v0 offset:204
	v_readlane_b32 s2, v254, 13
	s_getreg_b32 s2, hwreg(HW_REG_XCC_ID, 0, 4)
	s_waitcnt vmcnt(0)
	s_waitcnt lgkmcnt(0)
	v_readfirstlane_b32 s56, v2
	v_readfirstlane_b32 s57, v0
	v_readlane_b32 s3, v254, 14
	s_barrier
	s_mov_b64 s[0:1], exec
	v_readlane_b32 s4, v254, 9
	v_readlane_b32 s5, v254, 10
	s_and_b64 s[4:5], s[0:1], s[4:5]
	s_mov_b64 exec, s[4:5]
	s_cbranch_execz .LBB0_590
	s_add_i32 s59, s60, 0x20020
	v_mov_b32_e32 v0, s59
	s_waitcnt vmcnt(0) expcnt(0) lgkmcnt(0)
	ds_read_b32 v2, v0
	s_add_i32 s60, s60, 0x20024
	v_mov_b32_e32 v0, s60
	ds_read_b32 v0, v0
	s_and_b32 s58, s2, 15
	s_waitcnt lgkmcnt(1)
	v_cmp_ne_u32_e32 vcc, 0, v2
	s_cbranch_vccnz .LBB0_561
	s_add_u32 s2, s56, 0x4200
	s_addc_u32 s3, s57, 0
	s_add_u32 s4, s56, 0x4400
	s_addc_u32 s5, s57, 0
	s_add_u32 s6, s56, 0x4500
	s_addc_u32 s7, s57, 0
	s_add_u32 s8, s56, 0x4600
	s_addc_u32 s9, s57, 0
	s_add_u32 s10, s56, 0x4700
	s_addc_u32 s11, s57, 0
	s_add_u32 s12, s56, 0x4800
	s_addc_u32 s13, s57, 0
	s_add_u32 s14, s56, 0x4900
	s_addc_u32 s15, s57, 0
	s_add_u32 s16, s56, 0x4a00
	s_addc_u32 s17, s57, 0
	s_add_u32 s18, s56, 0x4b00
	s_addc_u32 s19, s57, 0
	s_add_u32 s20, s56, 0x4c00
	s_addc_u32 s21, s57, 0
	s_add_u32 s22, s56, 0x4d00
	s_addc_u32 s23, s57, 0
	s_add_u32 s24, s56, 0x4e00
	s_addc_u32 s25, s57, 0
	s_add_u32 s26, s56, 0x4f00
	s_addc_u32 s27, s57, 0
	s_add_u32 s28, s56, 0x5000
	s_addc_u32 s29, s57, 0
	s_add_u32 s30, s56, 0x5100
	s_addc_u32 s31, s57, 0
	s_add_u32 s34, s56, 0x5200
	s_addc_u32 s35, s57, 0
	s_add_u32 s36, s56, 0x5300
	s_addc_u32 s37, s57, 0
	s_mov_b32 s61, 1
	s_mov_b64 s[38:39], 0
	s_branch .LBB0_551

; #define LAS __attribute__((address_space(3)))
; #define lds fresh_lds(lds0)
; DI void conv_ffn(const float* wg, const float* wu, const float* wd, bf16_t* Wgu, bf16_t* Wd, LAS float* scr, int gw, int NGW, int lane) {
;     conv_matrix(FGU{wg, wu}, DM, 2 * DFF, Wgu, scr, gw, NGW, lane);
;     conv_matrix(FPlain{wd, DM}, DFF, DM, Wd, scr, gw, NGW, lane);
; }
; __global__ void __launch_bounds__(512) mega_fwd(Params P) {
;     ...
;         for (int rep = 0; rep < REP_G2; ++rep) { PHASE_PTRS; pg8::Gemm g{HN, Win, MTOK, NPROJ, DM, DM, DM}; pg8::StaticOrder S; S.init(MTOK, NPROJ, G, bid); pg8::EpiBf16<0> E{PROJ, NPROJ, NPROJ}; pg8::gemm_phase(lds, g, S, E, wv0); }
;         gsync(lds);
.LBB0_640:
	s_cmpk_lt_u32 s75, 0x80
	s_cbranch_scc1 .Lin_noconv
	v_readlane_b32 s0, v254, 12
	s_nop 3
	s_add_i32 s0, s0, 0x20108
	v_mov_b32_e32 v0, s0
	ds_read_b64 v[2:3], v0
	s_sub_i32 s7, s75, 0x80
	s_lshl_b32 s7, s7, 3
	s_add_i32 s7, s7, s74
	s_sub_i32 s6, s82, 0x80
	s_lshl_b32 s6, s6, 3
	s_mov_b32 s8, 0
	v_mov_b32_e32 v0, v1
	v_mbcnt_lo_u32_b32 v0, -1, v0
	v_mbcnt_hi_u32_b32 v11, -1, v0
	v_and_b32_e32 v10, 63, v11
	s_waitcnt lgkmcnt(0)
	v_readfirstlane_b32 s2, v2
	v_readfirstlane_b32 s3, v3
	v_lshlrev_b32_e32 v2, 3, v10
	s_branch .LBB0_540
.Lin_conv_ret:
.Lin_noconv:
	v_readlane_b32 s0, v254, 11
	v_readlane_b32 s1, v254, 12
	v_readlane_b32 s2, v254, 13
	s_mov_b32 s2, s1
	s_add_i32 s0, s2, 0x20040
	v_mov_b32_e32 v0, s0
	ds_read_b32 v2, v0 offset:200
	ds_read_b32 v0, v0 offset:204
	v_readlane_b32 s3, v254, 14
	s_getreg_b32 s3, hwreg(HW_REG_XCC_ID, 0, 4)
	s_waitcnt vmcnt(0)
	s_waitcnt lgkmcnt(0)
	v_readfirstlane_b32 s56, v2
	v_readfirstlane_b32 s57, v0
	s_waitcnt vmcnt(0)
	s_barrier
	s_mov_b64 s[0:1], exec
	v_readlane_b32 s4, v254, 9
	v_readlane_b32 s5, v254, 10
	s_and_b64 s[4:5], s[0:1], s[4:5]
	s_xor_b64 s[0:1], s[4:5], s[0:1]
	s_mov_b64 exec, s[4:5]
	s_cbranch_execz .LBB0_685
	s_add_i32 s59, s2, 0x20020
	v_mov_b32_e32 v0, s59
	s_waitcnt vmcnt(0) expcnt(0) lgkmcnt(0)
	ds_read_b32 v2, v0
	s_add_i32 s60, s2, 0x20024
	v_mov_b32_e32 v0, s60
	ds_read_b32 v0, v0
	s_and_b32 s58, s3, 15
	s_waitcnt lgkmcnt(1)
	v_cmp_ne_u32_e32 vcc, 0, v2
	s_cbranch_vccnz .LBB0_655
	s_add_u32 s2, s56, 0x4200
	s_addc_u32 s3, s57, 0
	s_add_u32 s4, s56, 0x4400
	s_addc_u32 s5, s57, 0
	s_add_u32 s6, s56, 0x4500
	s_addc_u32 s7, s57, 0
	s_add_u32 s8, s56, 0x4600
	s_addc_u32 s9, s57, 0
	s_add_u32 s10, s56, 0x4700
	s_addc_u32 s11, s57, 0
	s_add_u32 s12, s56, 0x4800
	s_addc_u32 s13, s57, 0
	s_add_u32 s14, s56, 0x4900
	s_addc_u32 s15, s57, 0
	s_add_u32 s16, s56, 0x4a00
	s_addc_u32 s17, s57, 0
	s_add_u32 s18, s56, 0x4b00
	s_addc_u32 s19, s57, 0
	s_add_u32 s20, s56, 0x4c00
	s_addc_u32 s21, s57, 0
	s_add_u32 s22, s56, 0x4d00
	s_addc_u32 s23, s57, 0
	s_add_u32 s24, s56, 0x4e00
	s_addc_u32 s25, s57, 0
	s_add_u32 s26, s56, 0x4f00
	s_addc_u32 s27, s57, 0
	s_add_u32 s28, s56, 0x5000
	s_addc_u32 s29, s57, 0
	s_add_u32 s30, s56, 0x5100
	s_addc_u32 s31, s57, 0
	s_add_u32 s34, s56, 0x5200
	s_addc_u32 s35, s57, 0
	s_add_u32 s36, s56, 0x5300
	s_addc_u32 s37, s57, 0
	s_mov_b32 s61, 1
	s_mov_b64 s[38:39], 0
	s_branch .LBB0_645

; #define FL_LSTORE(buf) do { *(LAS u32x4*)(lds + AT_K + (buf) * KBUF + srow * KP2 + sch * 16) = rk1; \
;         if (DQK == 96 && tid < 256) *(LAS u32x4*)(lds + AT_K + (buf) * KBUF + srow2 * KP2 + 128 + sch2 * 16) = rk2; \
;         *(LAS u32x4*)(lds + AT_V + (buf) * VBUF + srow * VP2 + sch * 16) = rv; } while (0)
; #define lds fresh_lds(lds0)
; template <int DQK, int MODE> ...
;     ...
;     FL_GLOAD(t0);
;     __syncthreads();
;     FL_LSTORE(0);
;     if (t0 + 1 < t1) FL_GLOAD(t0 + 1);
;     __syncthreads();
; __global__ void __launch_bounds__(512) mega_fwd(Params P) {
;     ...
;                     flash_unit<96, MODE_CAUSAL>(lds, wv0, QMLA + (rb + q0) * 576 + h * 96, 576, KVB + rb * 768 + h * 64, 768, PROJ + rb * NPROJ + PC_KR, NPROJ,
;                                                 KVB + rb * 768 + 384 + h * 64, 768, q0, 0, (q0 + 256) / 64, 0.10206207261596577f * LOG2E, (u32x4){}, 1.f, tot, nullptr, WSP(float, WS_ROPE));
.LBB0_1349:
	s_or_b64 exec, exec, s[0:1]
	flat_load_dwordx4 v[2:5], v[4:5] offset:768
	s_movk_i32 s0, 0xd0
	v_mul_lo_u32 v140, v15, s0
	v_lshlrev_b32_e32 v141, 4, v19
	v_add3_u32 v0, s28, v140, v141
	v_lshlrev_b32_e32 v142, 4, v18
	s_waitcnt lgkmcnt(0)
	s_barrier
	s_waitcnt vmcnt(0)
	ds_write_b128 v0, v[6:9]
	s_and_saveexec_b64 s[0:1], vcc
	s_xor_b64 s[0:1], exec, s[0:1]
	v_lshlrev_b32_e32 v142, 4, v18
	s_or_saveexec_b64 s[0:1], s[0:1]
	s_movk_i32 s30, 0xd0
	v_mul_lo_u32 v143, v14, s30
	s_xor_b64 exec, exec, s[0:1]
	v_add3_u32 v0, s28, v143, v142
	ds_write_b128 v0, v[90:93] offset:128
	s_or_b64 exec, exec, s[0:1]
	s_movk_i32 s0, 0x90
	v_mul_lo_u32 v0, v15, s0
	v_add3_u32 v144, s28, v0, v141
	ds_write_b128 v144, v[2:5] offset:53248
	v_add_u32_e32 v4, v16, v17
	v_mov_b32_e32 v0, 0x18000
	v_lshl_add_u32 v0, v4, 1, v0
	v_lshl_add_u64 v[2:3], s[8:9], 0, v[0:1]
	flat_load_dwordx4 v[94:97], v[2:3]
	s_and_saveexec_b64 s[0:1], vcc
	s_xor_b64 s[0:1], exec, s[0:1]
	v_mul_lo_u32 v13, v14, s69
	s_andn2_saveexec_b64 s[0:1], s[0:1]
	s_cbranch_execz .LBB0_1357
	s_mov_b32 s30, 0x50000
	v_add3_u32 v0, v13, v142, s30
	v_lshl_add_u64 v[6:7], s[26:27], 0, v[0:1]
	flat_load_dwordx4 v[90:93], v[6:7]
.LBB0_1357:
	s_or_b64 exec, exec, s[0:1]
	flat_load_dwordx4 v[98:101], v[2:3] offset:768
	v_mul_u32_u24_e32 v0, 0xd0, v11
	v_lshlrev_b32_e32 v2, 1, v10
	v_lshlrev_b32_e32 v139, 2, v12
	v_lshl_add_u32 v146, v12, 4, v0
	v_lshrrev_b32_e32 v0, 2, v10
	v_and_b32_e32 v2, 32, v2
	v_lshlrev_b32_e32 v3, 3, v10
	v_and_or_b32 v0, v0, 3, v139
	v_and_or_b32 v2, v3, 24, v2
	s_movk_i32 s0, 0x90
	s_addk_i32 s35, 0x2000
	v_mad_u32_u24 v145, v0, s0, v2
	s_mov_b32 s0, 0xa0000
	v_mov_b32_e32 v0, 0x30000
	v_mov_b32_e32 v16, v1
	v_mov_b32_e32 v17, v1
	s_lshr_b32 s31, s35, 6
	v_add3_u32 v134, v13, v142, s0
	v_lshl_add_u32 v0, v4, 1, v0
	v_mov_b32_e32 v2, v1
	v_mov_b32_e32 v3, v1
	v_mov_b32_e32 v4, v1
	v_mov_b32_e32 v5, v1
	v_mov_b32_e32 v6, v1
	v_mov_b32_e32 v7, v1
	v_mov_b32_e32 v8, v1
	v_mov_b32_e32 v9, v1
	v_mov_b32_e32 v10, v1
	v_mov_b32_e32 v11, v1
	v_mov_b32_e32 v12, v1
	v_mov_b32_e32 v13, v1
	v_mov_b32_e32 v14, v1
	v_mov_b32_e32 v15, v1
	v_mov_b64_e32 v[32:33], v[16:17]
	s_or_b32 s30, s29, 31
	s_add_i32 s35, s31, -1
	s_mov_b32 s36, 0
	v_mov_b32_e32 v137, 0
	v_mov_b32_e32 v138, 0xf149f2ca
	s_mov_b32 s37, 63
	v_mov_b64_e32 v[30:31], v[14:15]
	v_mov_b64_e32 v[28:29], v[12:13]
	v_mov_b64_e32 v[26:27], v[10:11]
	v_mov_b64_e32 v[24:25], v[8:9]
	v_mov_b64_e32 v[22:23], v[6:7]
	v_mov_b64_e32 v[20:21], v[4:5]
	v_mov_b64_e32 v[18:19], v[2:3]
	s_waitcnt vmcnt(0)
	s_add_i32 s46, s28, 0x3400
	v_add3_u32 v226, s46, v140, v141
	ds_write_b128 v226, v[94:97]
	v_add_u32_e32 v227, 0x2400, v144
	ds_write_b128 v227, v[98:101] offset:53248
	s_and_saveexec_b64 s[0:1], s[4:5]
	v_add3_u32 v226, s46, v143, v142
	ds_write_b128 v226, v[90:93] offset:128
	s_or_b64 exec, exec, s[0:1]
	v_lshl_add_u64 v[228:229], s[8:9], 0, v[0:1]
	global_load_dwordx4 v[94:97], v[228:229], off
	global_load_dwordx4 v[98:101], v[228:229], off offset:768
	v_add_u32_e32 v230, 0x18000, v0
	v_mov_b32_e32 v231, v1
	v_lshl_add_u64 v[230:231], s[8:9], 0, v[230:231]
	global_load_dwordx4 v[218:221], v[230:231], off
	global_load_dwordx4 v[234:237], v[230:231], off offset:768
	s_and_saveexec_b64 s[0:1], s[4:5]
	v_mov_b32_e32 v135, v1
	v_lshl_add_u64 v[238:239], s[26:27], 0, v[134:135]
	global_load_dwordx4 v[90:93], v[238:239], off
	v_add_u32_e32 v240, 0x50000, v134
	v_mov_b32_e32 v241, v1
	v_lshl_add_u64 v[240:241], s[26:27], 0, v[240:241]
	global_load_dwordx4 v[222:225], v[240:241], off
	s_or_b64 exec, exec, s[0:1]
	s_waitcnt lgkmcnt(0)
	s_barrier
	s_branch .LBB0_1360

; #define lds fresh_lds(lds0)
; template <int DQK, int MODE> ...
;     ...
;         const int cur = (t - t0) & 1;
;         const LAS unsigned char* Ks = lds + AT_K + cur * KBUF; const LAS unsigned char* Vs = lds + AT_V + cur * VBUF;
;         bool active = true;
;         if (MODE == MODE_CAUSAL || MODE == MODE_SEL || MODE == MODE_WIN) active = (64 * t <= qmax);
;         if (MODE == MODE_WIN) active = active && (64 * t + 63 + 512 > qmin);
;         if (MODE == MODE_CMP) active = (16 * (64 * t) + 31 <= qmax);
;         if (active) {
;             f32x16 s[2];
;             bf16x8 ka[2][NKS]; s16x4 vlo[2][2][2], vhi[2][2][2];
;             {
;                 const unsigned kaddr = (unsigned)(unsigned long)(lds + AT_K + cur * KBUF) + (unsigned)(r32 * KP2 + hi * 16);
;                 const unsigned vaddr = (unsigned)(unsigned long)(lds + AT_V + cur * VBUF) + (unsigned)((4 * hi + ((lane & 15) >> 2)) * VP2 + 32 * ((lane >> 4) & 1) + 8 * (lane & 3));
; #pragma unroll
;                 for (int kb = 0; kb < 2; ++kb)
; #pragma unroll
;                     for (int ks = 0; ks < NKS; ++ks) asm volatile("ds_read_b128 %0, %1 offset:%2" : "=v"(ka[kb][ks]) : "v"(kaddr), "n"(kb * 32 * KP2 + ks * 32) : "memory");
; #pragma unroll
;                 for (int s2 = 0; s2 < 2; ++s2)
; #pragma unroll
;                     for (int d0 = 0; d0 < 2; ++d0) {
;                         asm volatile("ds_read_b64_tr_b16 %0, %1 offset:%2" : "=v"(vlo[0][s2][d0]) : "v"(vaddr), "n"(16 * s2 * VP2 + 64 * d0) : "memory");
;                         asm volatile("ds_read_b64_tr_b16 %0, %1 offset:%2" : "=v"(vhi[0][s2][d0]) : "v"(vaddr), "n"(16 * s2 * VP2 + 64 * d0 + 8 * VP2) : "memory");
;                     }
;                 asm volatile("s_waitcnt lgkmcnt(8)" ::: "memory");
; #pragma unroll
;                 for (int kb = 0; kb < 2; ++kb)
; #pragma unroll
;                     for (int ks = 0; ks < NKS; ++ks) asm volatile("" : "+v"(ka[kb][ks]));
;                 s[0] = (f32x16){}; s[1] = (f32x16){};
;                 __builtin_amdgcn_s_setprio(1);
; #pragma unroll
;                 for (int ks = 0; ks < NKS; ++ks) { s[0] = MFMA32(ka[0][ks], qf[ks], s[0]); s[1] = MFMA32(ka[1][ks], qf[ks], s[1]); }
;                 __builtin_amdgcn_s_setprio(0);
; #pragma unroll
;                 for (int s2 = 0; s2 < 2; ++s2)
; #pragma unroll
;                     for (int d0 = 0; d0 < 2; ++d0) {
.LBB0_1360:
	s_and_b32 s0, s36, 3
	s_sub_i32 s1, s37, 63
	s_cmp_gt_i32 s1, s30
	s_cbranch_scc1 .LBB0_1366
	s_mul_i32 s45, s0, 0x3400
	s_add_i32 s45, s28, s45
	v_add_u32_e32 v38, s45, v146
	ds_read_b128 v[50:53], v38 offset:0
	ds_read_b128 v[118:121], v38 offset:32
	ds_read_b128 v[122:125], v38 offset:64
	ds_read_b128 v[126:129], v38 offset:0x60
	ds_read_b128 v[148:151], v38 offset:0x80
	ds_read_b128 v[152:155], v38 offset:0xa0
	ds_read_b128 v[34:37], v38 offset:0x1a00
	ds_read_b128 v[54:57], v38 offset:0x1a20
	ds_read_b128 v[58:61], v38 offset:0x1a40
	s_mul_i32 s1, s0, 0x2400
	ds_read_b128 v[62:65], v38 offset:0x1a60
	s_add_i32 s1, s28, s1
	ds_read_b128 v[130:133], v38 offset:0x1a80
	s_add_i32 s1, s1, 0xd000
	ds_read_b128 v[158:161], v38 offset:0x1aa0
	v_add_u32_e32 v135, s1, v145
	ds_read_b64_tr_b16 v[114:115], v135 offset:0
	ds_read_b64_tr_b16 v[116:117], v135 offset:0x480
	ds_read_b64_tr_b16 v[110:111], v135 offset:64
	ds_read_b64_tr_b16 v[112:113], v135 offset:0x4c0
	ds_read_b64_tr_b16 v[106:107], v135 offset:0x900
	ds_read_b64_tr_b16 v[108:109], v135 offset:0xd80
	ds_read_b64_tr_b16 v[102:103], v135 offset:0x940
	ds_read_b64_tr_b16 v[104:105], v135 offset:0xdc0
	s_waitcnt lgkmcnt(8)
	s_setprio 1
	v_mfma_f32_32x32x16_bf16 v[34:49], v[34:37], v[86:89], 0
	v_mfma_f32_32x32x16_bf16 v[34:49], v[54:57], v[82:85], v[34:49]
	v_mfma_f32_32x32x16_bf16 v[34:49], v[58:61], v[78:81], v[34:49]
	v_mfma_f32_32x32x16_bf16 v[34:49], v[62:65], v[74:77], v[34:49]
	v_mfma_f32_32x32x16_bf16 v[34:49], v[130:133], v[66:69], v[34:49]
	v_mfma_f32_32x32x16_bf16 v[34:49], v[158:161], v[70:73], v[34:49]
	s_setprio 0
	v_mfma_f32_32x32x16_bf16 v[50:65], v[50:53], v[86:89], 0
	ds_read_b64_tr_b16 v[130:131], v135 offset:0x1200
	ds_read_b64_tr_b16 v[132:133], v135 offset:0x1680
	s_cmp_le_i32 s37, s29
	v_mfma_f32_32x32x16_bf16 v[50:65], v[118:121], v[82:85], v[50:65]
	v_mfma_f32_32x32x16_bf16 v[50:65], v[122:125], v[78:81], v[50:65]
	v_mfma_f32_32x32x16_bf16 v[50:65], v[126:129], v[74:77], v[50:65]
	ds_read_b64_tr_b16 v[126:127], v135 offset:0x1240
	ds_read_b64_tr_b16 v[128:129], v135 offset:0x16c0
	ds_read_b64_tr_b16 v[122:123], v135 offset:0x1b00
	ds_read_b64_tr_b16 v[124:125], v135 offset:0x1f80
	ds_read_b64_tr_b16 v[118:119], v135 offset:0x1b40
	ds_read_b64_tr_b16 v[120:121], v135 offset:0x1fc0
	v_mfma_f32_32x32x16_bf16 v[50:65], v[148:151], v[66:69], v[50:65]
	v_mfma_f32_32x32x16_bf16 v[50:65], v[152:155], v[70:73], v[50:65]
	s_cbranch_scc1 .LBB0_1363
	v_add_u32_e32 v135, s37, v139
	v_subrev_u32_e32 v147, 63, v135
	v_cmp_le_i32_e32 vcc, v147, v136
	s_nop 7
	v_cndmask_b32_e32 v50, v204, v50, vcc
	v_cmp_lt_i32_e32 vcc, v147, v136
	v_subrev_u32_e32 v147, 61, v135
	s_nop 0
	v_cndmask_b32_e32 v51, v204, v51, vcc
	v_cmp_le_i32_e32 vcc, v147, v136
	v_subrev_u32_e32 v147, 60, v135
	s_nop 0
	v_cndmask_b32_e32 v52, v204, v52, vcc
	v_cmp_le_i32_e32 vcc, v147, v136
	v_subrev_u32_e32 v147, 55, v135
	s_nop 0
	v_cndmask_b32_e32 v53, v204, v53, vcc
	v_cmp_le_i32_e32 vcc, v147, v136
	v_subrev_u32_e32 v147, 54, v135
	s_nop 0
	v_cndmask_b32_e32 v54, v204, v54, vcc
	v_cmp_le_i32_e32 vcc, v147, v136
	v_subrev_u32_e32 v147, 53, v135
	s_nop 0
	v_cndmask_b32_e32 v55, v204, v55, vcc
	v_cmp_le_i32_e32 vcc, v147, v136
	v_subrev_u32_e32 v147, 52, v135
	s_nop 0
	v_cndmask_b32_e32 v56, v204, v56, vcc
	v_cmp_le_i32_e32 vcc, v147, v136
	v_subrev_u32_e32 v147, 47, v135
	s_nop 0
	v_cndmask_b32_e32 v57, v204, v57, vcc
	v_cmp_le_i32_e32 vcc, v147, v136
	v_subrev_u32_e32 v147, 46, v135
	s_nop 0
	v_cndmask_b32_e32 v58, v204, v58, vcc
	v_cmp_le_i32_e32 vcc, v147, v136
	v_subrev_u32_e32 v147, 45, v135
	s_nop 0
	v_cndmask_b32_e32 v59, v204, v59, vcc
	v_cmp_le_i32_e32 vcc, v147, v136
	v_subrev_u32_e32 v147, 44, v135
	s_nop 0
	v_cndmask_b32_e32 v60, v204, v60, vcc
	v_cmp_le_i32_e32 vcc, v147, v136
	v_subrev_u32_e32 v147, 39, v135
	s_nop 0
	v_cndmask_b32_e32 v61, v204, v61, vcc
	v_cmp_le_i32_e32 vcc, v147, v136
	v_subrev_u32_e32 v147, 38, v135
	s_nop 0
	v_cndmask_b32_e32 v62, v204, v62, vcc
	v_cmp_le_i32_e32 vcc, v147, v136
	v_subrev_u32_e32 v147, 37, v135
	s_nop 0
	v_cndmask_b32_e32 v63, v204, v63, vcc
	v_cmp_le_i32_e32 vcc, v147, v136
	v_subrev_u32_e32 v147, 36, v135
	s_nop 0
	v_cndmask_b32_e32 v64, v204, v64, vcc
	v_cmp_le_i32_e32 vcc, v147, v136
	v_subrev_u32_e32 v147, 31, v135
	s_nop 0
	v_cndmask_b32_e32 v65, v204, v65, vcc
	v_cmp_le_i32_e32 vcc, v147, v136
	v_subrev_u32_e32 v147, 30, v135
	s_nop 0
	v_cndmask_b32_e32 v34, v204, v34, vcc
	v_cmp_le_i32_e32 vcc, v147, v136
	v_subrev_u32_e32 v147, 29, v135
	s_nop 0
	v_cndmask_b32_e32 v35, v204, v35, vcc
	v_cmp_le_i32_e32 vcc, v147, v136
	v_subrev_u32_e32 v147, 28, v135
	s_nop 0
	v_cndmask_b32_e32 v36, v204, v36, vcc
	v_cmp_le_i32_e32 vcc, v147, v136
	v_subrev_u32_e32 v147, 23, v135
	s_nop 0
	v_cndmask_b32_e32 v37, v204, v37, vcc
	v_cmp_le_i32_e32 vcc, v147, v136
	v_subrev_u32_e32 v147, 22, v135
	s_nop 0
	v_cndmask_b32_e32 v38, v204, v38, vcc
	v_cmp_le_i32_e32 vcc, v147, v136
	v_subrev_u32_e32 v147, 21, v135
	s_nop 0
	v_cndmask_b32_e32 v39, v204, v39, vcc
	v_cmp_le_i32_e32 vcc, v147, v136
	v_subrev_u32_e32 v147, 20, v135
	s_nop 0
	v_cndmask_b32_e32 v40, v204, v40, vcc
	v_cmp_le_i32_e32 vcc, v147, v136
	v_add_u32_e32 v147, -15, v135
	s_nop 0
	v_cndmask_b32_e32 v41, v204, v41, vcc
	v_cmp_le_i32_e32 vcc, v147, v136
	v_add_u32_e32 v147, -14, v135
	s_nop 0
	v_cndmask_b32_e32 v42, v204, v42, vcc
	v_cmp_le_i32_e32 vcc, v147, v136
	v_add_u32_e32 v147, -13, v135
	s_nop 0
	v_cndmask_b32_e32 v43, v204, v43, vcc
	v_cmp_le_i32_e32 vcc, v147, v136
	v_add_u32_e32 v147, -12, v135
	s_nop 0
	v_cndmask_b32_e32 v44, v204, v44, vcc
	v_cmp_le_i32_e32 vcc, v147, v136
	v_add_u32_e32 v147, -7, v135
	s_nop 0
	v_cndmask_b32_e32 v45, v204, v45, vcc
	v_cmp_le_i32_e32 vcc, v147, v136
	v_add_u32_e32 v147, -6, v135
	s_nop 0
	v_cndmask_b32_e32 v46, v204, v46, vcc
	v_cmp_le_i32_e32 vcc, v147, v136
	v_add_u32_e32 v147, -5, v135
	v_add_u32_e32 v135, -4, v135
	v_cndmask_b32_e32 v47, v204, v47, vcc
	v_cmp_le_i32_e32 vcc, v147, v136
	s_nop 1
	v_cndmask_b32_e32 v48, v204, v48, vcc
	v_cmp_le_i32_e32 vcc, v135, v136
	s_nop 1
	v_cndmask_b32_e32 v49, v204, v49, vcc

; #define FL_LSTORE(buf) do { *(LAS u32x4*)(lds + AT_K + (buf) * KBUF + srow * KP2 + sch * 16) = rk1; \
;         if (DQK == 96 && tid < 256) *(LAS u32x4*)(lds + AT_K + (buf) * KBUF + srow2 * KP2 + 128 + sch2 * 16) = rk2; \
;         *(LAS u32x4*)(lds + AT_V + (buf) * VBUF + srow * VP2 + sch * 16) = rv; } while (0)
; template <int DQK, int MODE> ...
;     ...
;         if (t + 1 < t1) { FL_LSTORE(cur ^ 1); if (t + 2 < t1) FL_GLOAD(t + 2); }
;         __syncthreads();
.LBB0_1366:
	s_bitcmp1_b32 s36, 0
	s_cbranch_scc0 .Lmla_even
	s_add_i32 s45, s36, 1
	s_and_b32 s45, s45, 3
	s_mul_i32 s0, s45, 0x3400
	s_add_i32 s46, s28, s0
	s_mulk_i32 s45, 0x2400
	s_waitcnt vmcnt(0)
	v_add3_u32 v226, s46, v140, v141
	ds_write_b128 v226, v[94:97]
	v_add_u32_e32 v227, s45, v144
	ds_write_b128 v227, v[98:101] offset:53248
	s_and_saveexec_b64 s[0:1], s[4:5]
	v_add3_u32 v226, s46, v143, v142
	ds_write_b128 v226, v[90:93] offset:128
	s_or_b64 exec, exec, s[0:1]
	s_add_i32 s45, s36, 2
	s_and_b32 s45, s45, 3
	s_mul_i32 s0, s45, 0x3400
	s_add_i32 s46, s28, s0
	s_mulk_i32 s45, 0x2400
	v_add3_u32 v226, s46, v140, v141
	ds_write_b128 v226, v[218:221]
	v_add_u32_e32 v227, s45, v144
	ds_write_b128 v227, v[234:237] offset:53248
	s_and_saveexec_b64 s[0:1], s[4:5]
	v_add3_u32 v226, s46, v143, v142
	ds_write_b128 v226, v[222:225] offset:128
	s_or_b64 exec, exec, s[0:1]
	s_add_i32 s0, s36, 3
	s_cmp_ge_u32 s0, s31
	s_cbranch_scc1 .LBB0_1359
	v_add_u32_e32 v228, 0x18000, v0
	v_mov_b32_e32 v229, v1
	v_lshl_add_u64 v[228:229], s[8:9], 0, v[228:229]
	global_load_dwordx4 v[94:97], v[228:229], off
	global_load_dwordx4 v[98:101], v[228:229], off offset:768
	v_add_u32_e32 v230, 0x30000, v0
	v_mov_b32_e32 v231, v1
	v_lshl_add_u64 v[230:231], s[8:9], 0, v[230:231]
	global_load_dwordx4 v[218:221], v[230:231], off
	global_load_dwordx4 v[234:237], v[230:231], off offset:768
	s_and_saveexec_b64 s[0:1], s[4:5]
	v_add_u32_e32 v238, 0x50000, v134
	v_mov_b32_e32 v239, v1
	v_lshl_add_u64 v[238:239], s[26:27], 0, v[238:239]
	global_load_dwordx4 v[90:93], v[238:239], off
	v_add_u32_e32 v240, 0xa0000, v134
	v_mov_b32_e32 v241, v1
	v_lshl_add_u64 v[240:241], s[26:27], 0, v[240:241]
	global_load_dwordx4 v[222:225], v[240:241], off
	s_or_b64 exec, exec, s[0:1]
	s_branch .LBB0_1359
.Lmla_even:
	s_add_i32 s36, s36, 1
	s_add_i32 s37, s37, 64
	v_add_u32_e32 v134, 0x50000, v134
	s_cmp_eq_u32 s35, s36
	v_add_u32_e32 v0, 0x18000, v0
	s_cbranch_scc1 .LBB0_1388
	s_branch .LBB0_1360

; #define lds fresh_lds(lds0)
; template <int DQK, int MODE> ...
;     ...
;         const int cur = (t - t0) & 1;
;         const LAS unsigned char* Ks = lds + AT_K + cur * KBUF; const LAS unsigned char* Vs = lds + AT_V + cur * VBUF;
;         bool active = true;
;         if (MODE == MODE_CAUSAL || MODE == MODE_SEL || MODE == MODE_WIN) active = (64 * t <= qmax);
;         if (MODE == MODE_WIN) active = active && (64 * t + 63 + 512 > qmin);
;         if (MODE == MODE_CMP) active = (16 * (64 * t) + 31 <= qmax);
;         if (active) {
;             f32x16 s[2];
;             bf16x8 ka[2][NKS]; s16x4 vlo[2][2][2], vhi[2][2][2];
;             {
;                 const unsigned kaddr = (unsigned)(unsigned long)(lds + AT_K + cur * KBUF) + (unsigned)(r32 * KP2 + hi * 16);
;                 const unsigned vaddr = (unsigned)(unsigned long)(lds + AT_V + cur * VBUF) + (unsigned)((4 * hi + ((lane & 15) >> 2)) * VP2 + 32 * ((lane >> 4) & 1) + 8 * (lane & 3));
; #pragma unroll
;                 for (int kb = 0; kb < 2; ++kb)
; #pragma unroll
;                     for (int ks = 0; ks < NKS; ++ks) asm volatile("ds_read_b128 %0, %1 offset:%2" : "=v"(ka[kb][ks]) : "v"(kaddr), "n"(kb * 32 * KP2 + ks * 32) : "memory");
; #pragma unroll
;                 for (int s2 = 0; s2 < 2; ++s2)
; #pragma unroll
;                     for (int d0 = 0; d0 < 2; ++d0) {
;                         asm volatile("ds_read_b64_tr_b16 %0, %1 offset:%2" : "=v"(vlo[0][s2][d0]) : "v"(vaddr), "n"(16 * s2 * VP2 + 64 * d0) : "memory");
;                         asm volatile("ds_read_b64_tr_b16 %0, %1 offset:%2" : "=v"(vhi[0][s2][d0]) : "v"(vaddr), "n"(16 * s2 * VP2 + 64 * d0 + 8 * VP2) : "memory");
;                     }
;                 asm volatile("s_waitcnt lgkmcnt(8)" ::: "memory");
; #pragma unroll
;                 for (int kb = 0; kb < 2; ++kb)
; #pragma unroll
;                     for (int ks = 0; ks < NKS; ++ks) asm volatile("" : "+v"(ka[kb][ks]));
;                 s[0] = (f32x16){}; s[1] = (f32x16){};
;                 __builtin_amdgcn_s_setprio(1);
; #pragma unroll
;                 for (int ks = 0; ks < NKS; ++ks) { s[0] = MFMA32(ka[0][ks], qf[ks], s[0]); s[1] = MFMA32(ka[1][ks], qf[ks], s[1]); }
;                 __builtin_amdgcn_s_setprio(0);
; #pragma unroll
;                 for (int s2 = 0; s2 < 2; ++s2)
; #pragma unroll
;                     for (int d0 = 0; d0 < 2; ++d0) {
.LBB0_1388:
	s_lshl_b32 s0, s35, 6
	s_cmp_gt_i32 s0, s30
	s_cbranch_scc1 .LBB0_1394
	s_and_b32 s1, s35, 3
	s_mul_i32 s4, s1, 0x2400
	s_mulk_i32 s1, 0x3400
	s_add_i32 s1, s28, s1
	v_add_u32_e32 v0, s1, v146
	ds_read_b128 v[50:53], v0 offset:0
	ds_read_b128 v[106:109], v0 offset:32
	ds_read_b128 v[110:113], v0 offset:64
	ds_read_b128 v[114:117], v0 offset:0x60
	ds_read_b128 v[118:121], v0 offset:0x80
	ds_read_b128 v[122:125], v0 offset:0xa0
	ds_read_b128 v[34:37], v0 offset:0x1a00
	ds_read_b128 v[54:57], v0 offset:0x1a20
	ds_read_b128 v[58:61], v0 offset:0x1a40
	ds_read_b128 v[62:65], v0 offset:0x1a60
	s_add_i32 s1, s28, s4
	ds_read_b128 v[126:129], v0 offset:0x1a80
	s_add_i32 s1, s1, 0xd000
	ds_read_b128 v[130:133], v0 offset:0x1aa0
	v_add_u32_e32 v0, s1, v145
	ds_read_b64_tr_b16 v[102:103], v0 offset:0
	ds_read_b64_tr_b16 v[104:105], v0 offset:0x480
	s_waitcnt vmcnt(0)
	ds_read_b64_tr_b16 v[98:99], v0 offset:64
	ds_read_b64_tr_b16 v[100:101], v0 offset:0x4c0
	ds_read_b64_tr_b16 v[94:95], v0 offset:0x900
	ds_read_b64_tr_b16 v[96:97], v0 offset:0xd80
	ds_read_b64_tr_b16 v[90:91], v0 offset:0x940
	ds_read_b64_tr_b16 v[92:93], v0 offset:0xdc0
	s_waitcnt lgkmcnt(8)
	s_setprio 1
	v_mfma_f32_32x32x16_bf16 v[34:49], v[34:37], v[86:89], 0
	v_mfma_f32_32x32x16_bf16 v[34:49], v[54:57], v[82:85], v[34:49]
	v_mfma_f32_32x32x16_bf16 v[34:49], v[58:61], v[78:81], v[34:49]
	v_mfma_f32_32x32x16_bf16 v[34:49], v[62:65], v[74:77], v[34:49]
	v_mfma_f32_32x32x16_bf16 v[34:49], v[126:129], v[66:69], v[34:49]
	v_mfma_f32_32x32x16_bf16 v[34:49], v[130:133], v[70:73], v[34:49]
	s_setprio 0
	v_mfma_f32_32x32x16_bf16 v[50:65], v[50:53], v[86:89], 0
	s_or_b32 s1, s0, 63
	s_cmp_le_i32 s1, s29
	v_mfma_f32_32x32x16_bf16 v[50:65], v[106:109], v[82:85], v[50:65]
	ds_read_b64_tr_b16 v[82:83], v0 offset:0x1200
	ds_read_b64_tr_b16 v[84:85], v0 offset:0x1680
	v_mfma_f32_32x32x16_bf16 v[50:65], v[110:113], v[78:81], v[50:65]
	ds_read_b64_tr_b16 v[78:79], v0 offset:0x1240
	ds_read_b64_tr_b16 v[80:81], v0 offset:0x16c0
	v_mfma_f32_32x32x16_bf16 v[50:65], v[114:117], v[74:77], v[50:65]
	ds_read_b64_tr_b16 v[74:75], v0 offset:0x1b00
	ds_read_b64_tr_b16 v[76:77], v0 offset:0x1f80
	v_mfma_f32_32x32x16_bf16 v[50:65], v[118:121], v[66:69], v[50:65]
	ds_read_b64_tr_b16 v[66:67], v0 offset:0x1b40
	ds_read_b64_tr_b16 v[68:69], v0 offset:0x1fc0
	v_mfma_f32_32x32x16_bf16 v[50:65], v[122:125], v[70:73], v[50:65]
	s_cbranch_scc1 .LBB0_1391
	v_or_b32_e32 v0, s0, v139
	v_cmp_le_i32_e32 vcc, v0, v136
	v_or_b32_e32 v70, 2, v0
	s_nop 7
	v_cndmask_b32_e32 v50, v204, v50, vcc
	v_cmp_lt_i32_e32 vcc, v0, v136
	s_nop 1
	v_cndmask_b32_e32 v51, v204, v51, vcc
	v_cmp_le_i32_e32 vcc, v70, v136
	v_or_b32_e32 v70, 3, v0
	s_nop 0
	v_cndmask_b32_e32 v52, v204, v52, vcc
	v_cmp_le_i32_e32 vcc, v70, v136
	v_or_b32_e32 v70, 8, v0
	s_nop 0
	v_cndmask_b32_e32 v53, v204, v53, vcc
	v_cmp_le_i32_e32 vcc, v70, v136
	v_or_b32_e32 v70, 9, v0
	s_nop 0
	v_cndmask_b32_e32 v54, v204, v54, vcc
	v_cmp_le_i32_e32 vcc, v70, v136
	v_or_b32_e32 v70, 10, v0
	s_nop 0
	v_cndmask_b32_e32 v55, v204, v55, vcc
	v_cmp_le_i32_e32 vcc, v70, v136
	v_or_b32_e32 v70, 11, v0
	s_nop 0
	v_cndmask_b32_e32 v56, v204, v56, vcc
	v_cmp_le_i32_e32 vcc, v70, v136
	v_or_b32_e32 v70, 16, v0
	s_nop 0
	v_cndmask_b32_e32 v57, v204, v57, vcc
	v_cmp_le_i32_e32 vcc, v70, v136
	v_or_b32_e32 v70, 17, v0
	s_nop 0
	v_cndmask_b32_e32 v58, v204, v58, vcc
	v_cmp_le_i32_e32 vcc, v70, v136
	v_or_b32_e32 v70, 18, v0
	s_nop 0
	v_cndmask_b32_e32 v59, v204, v59, vcc
	v_cmp_le_i32_e32 vcc, v70, v136
	v_or_b32_e32 v70, 19, v0
	s_nop 0
	v_cndmask_b32_e32 v60, v204, v60, vcc
	v_cmp_le_i32_e32 vcc, v70, v136
	v_or_b32_e32 v70, 24, v0
	s_nop 0
	v_cndmask_b32_e32 v61, v204, v61, vcc
	v_cmp_le_i32_e32 vcc, v70, v136
	v_or_b32_e32 v70, 25, v0
	s_nop 0
	v_cndmask_b32_e32 v62, v204, v62, vcc
	v_cmp_le_i32_e32 vcc, v70, v136
	v_or_b32_e32 v70, 26, v0
	s_nop 0
	v_cndmask_b32_e32 v63, v204, v63, vcc
	v_cmp_le_i32_e32 vcc, v70, v136
	v_or_b32_e32 v70, 27, v0
	s_nop 0
	v_cndmask_b32_e32 v64, v204, v64, vcc
	v_cmp_le_i32_e32 vcc, v70, v136
	v_or_b32_e32 v70, 32, v0
	s_nop 0
	v_cndmask_b32_e32 v65, v204, v65, vcc
	v_cmp_le_i32_e32 vcc, v70, v136
	v_or_b32_e32 v70, 33, v0
	s_nop 0
	v_cndmask_b32_e32 v34, v204, v34, vcc
	v_cmp_le_i32_e32 vcc, v70, v136
	v_or_b32_e32 v70, 34, v0
	s_nop 0
	v_cndmask_b32_e32 v35, v204, v35, vcc
	v_cmp_le_i32_e32 vcc, v70, v136
	v_or_b32_e32 v70, 35, v0
	s_nop 0
	v_cndmask_b32_e32 v36, v204, v36, vcc
	v_cmp_le_i32_e32 vcc, v70, v136
	v_or_b32_e32 v70, 40, v0
	s_nop 0
	v_cndmask_b32_e32 v37, v204, v37, vcc
	v_cmp_le_i32_e32 vcc, v70, v136
	v_or_b32_e32 v70, 41, v0
	s_nop 0
	v_cndmask_b32_e32 v38, v204, v38, vcc
	v_cmp_le_i32_e32 vcc, v70, v136
	v_or_b32_e32 v70, 42, v0
	s_nop 0
	v_cndmask_b32_e32 v39, v204, v39, vcc
	v_cmp_le_i32_e32 vcc, v70, v136
	v_or_b32_e32 v70, 43, v0
	s_nop 0
	v_cndmask_b32_e32 v40, v204, v40, vcc
	v_cmp_le_i32_e32 vcc, v70, v136
	v_or_b32_e32 v70, 48, v0
	s_nop 0
	v_cndmask_b32_e32 v41, v204, v41, vcc
	v_cmp_le_i32_e32 vcc, v70, v136
	v_or_b32_e32 v70, 49, v0
	s_nop 0
	v_cndmask_b32_e32 v42, v204, v42, vcc
	v_cmp_le_i32_e32 vcc, v70, v136
	v_or_b32_e32 v70, 50, v0
	s_nop 0
	v_cndmask_b32_e32 v43, v204, v43, vcc
	v_cmp_le_i32_e32 vcc, v70, v136
	v_or_b32_e32 v70, 51, v0
	s_nop 0
	v_cndmask_b32_e32 v44, v204, v44, vcc
	v_cmp_le_i32_e32 vcc, v70, v136
	v_or_b32_e32 v70, 56, v0
	s_nop 0
	v_cndmask_b32_e32 v45, v204, v45, vcc
	v_cmp_le_i32_e32 vcc, v70, v136
	v_or_b32_e32 v70, 57, v0
	s_nop 0
	v_cndmask_b32_e32 v46, v204, v46, vcc
	v_cmp_le_i32_e32 vcc, v70, v136
	v_or_b32_e32 v70, 58, v0
	v_or_b32_e32 v0, 59, v0
	v_cndmask_b32_e32 v47, v204, v47, vcc
	v_cmp_le_i32_e32 vcc, v70, v136
	s_nop 1
	v_cndmask_b32_e32 v48, v204, v48, vcc
	v_cmp_le_i32_e32 vcc, v0, v136
	s_nop 1
	v_cndmask_b32_e32 v49, v204, v49, vcc
